# P1: first K-loop iteration of every tile after the first peeled: As[1][1] stage of the next tile hoisted above the epilogue stores and the first three vmcnt waits relaxed to 16 so the tile-output stor
# speedup vs baseline: 1.0052x; 1.0052x over previous
; #define PG8_STAGE(bufoff, gbase, voff) do { _Pragma("unroll") for (int _i = 0; _i < 2; ++_i) \
;         __builtin_amdgcn_global_load_lds((const unsigned*)((const char*)(gbase) + (voff)[_i]), (PG8_LAS unsigned*)(lds + (bufoff) + ldsw + _i * 8192), 16, 0, 0); } while (0)
; #define PG8_LDA(dst, b, h) do { _Pragma("unroll") for (int m = 0; m < 4; ++m) _Pragma("unroll") for (int k = 0; k < 2; ++k) dst[m][k] = *(const PG8_LAS bf16x8*)(lds + PG8_SA(b, h) + aoff + m * 2048 + k * 1024); } while (0)
; #define PG8_LDB(dst, b, h) do { _Pragma("unroll") for (int n = 0; n < 2; ++n) _Pragma("unroll") for (int k = 0; k < 2; ++k) dst[n][k] = *(const PG8_LAS bf16x8*)(lds + PG8_SB(b, h) + boff + n * 2048 + k * 1024); } while (0)
; #define PG8_MMA(ai, bj, At, Bt) do { __builtin_amdgcn_s_setprio(1); _Pragma("unroll") for (int m = 0; m < 4; ++m) _Pragma("unroll") for (int n = 0; n < 2; ++n) _Pragma("unroll") for (int k = 0; k < 2; ++k) \
;         acc[ai][bj][m][n] = __builtin_amdgcn_mfma_f32_16x16x32_bf16(Bt[n][k], At[m][k], acc[ai][bj][m][n], 0, 0, 0); __builtin_amdgcn_s_setprio(0); } while (0)
; #define PG8_WAIT_V(n) asm volatile("s_waitcnt vmcnt(" #n ")" ::: "memory")
; #define PG8_BAR __builtin_amdgcn_s_barrier()
; template <class Epi, class Sched, bool ALIGN_EPI = false, bool SP2 = false>
; __device__ __forceinline__ void gemm_phase(PG8_LAS unsigned char* lds, const Gemm g, const Sched& S, const Epi& E) {
;     ...
;         for (int t = 0; t < nt; t += 2) {
;             const bool last = (t == nt - 2);
;             const char* a1 = cA + (size_t)(t + 1) * kstep;
;             const char* a2 = last ? nA : cA + (size_t)(t + 2) * kstep; const char* b2 = last ? nB : cB + (size_t)(t + 2) * kstep;
;             const char* a3 = a2 + kstep; const char* b3 = b2 + kstep;
;             if (last && has_next) S.a_ready(nxt);
;             if constexpr (SP2) {
;             PG8_LDB(B0, 0, 0); PG8_LDB(B1, 0, 1); PG8_SCHED; PG8_LDA(At, 0, 0); PG8_STAGE(PG8_SA(1, 1), a1 + hstep, voffA);
;             PG8_WAIT_V(8); PG8_WAIT_L(0); PG8_BAR; PG8_MMA(0, 0, At, B0); PG8_MMA(0, 1, At, B1); PG8_BAR; PG8_SCHED;
;     ...
; #pragma unroll
;         for (int a = 0; a < 2; ++a)
; #pragma unroll
;             for (int b = 0; b < 2; ++b)
; #pragma unroll
;                 for (int m = 0; m < 4; ++m)
; #pragma unroll
;                     for (int n = 0; n < 2; ++n) acc[a][b][m][n] = (f32x4){0.f, 0.f, 0.f, 0.f};
.LBB0_67:
	s_ashr_i32 s75, s74, 31
	s_lshl_b64 s[76:77], s[74:75], 20
	s_add_u32 s76, s90, s76
	s_addc_u32 s77, s91, s77
	s_and_b64 s[78:79], s[10:11], exec
	s_cselect_b32 s1, s77, s83
	s_cselect_b32 s75, s76, s82
	s_ashr_i32 s73, s72, 31
	s_lshl_b64 s[78:79], s[72:73], 20
	s_add_u32 s78, s58, s78
	s_addc_u32 s79, s59, s79
	s_and_b64 s[86:87], s[10:11], exec
	s_cselect_b32 s73, s79, s85
	s_cselect_b32 s81, s78, s84
	s_add_u32 s82, s82, 0x80080
	s_addc_u32 s83, s83, 0
	s_add_u32 vcc_lo, s84, 0x100
	s_addc_u32 vcc_hi, s85, 0
	s_mov_b32 s29, -2
	v_mov_b64_e32 v[0:1], 0
	v_mov_b64_e32 v[2:3], 0
	v_mov_b64_e32 v[4:5], 0
	v_mov_b64_e32 v[6:7], 0
	v_mov_b64_e32 v[8:9], 0
	v_mov_b64_e32 v[10:11], 0
	v_mov_b64_e32 v[12:13], 0
	v_mov_b64_e32 v[14:15], 0
	v_mov_b64_e32 v[16:17], 0
	v_mov_b64_e32 v[18:19], 0
	v_mov_b64_e32 v[20:21], 0
	v_mov_b64_e32 v[22:23], 0
	v_mov_b64_e32 v[24:25], 0
	v_mov_b64_e32 v[26:27], 0
	v_mov_b64_e32 v[28:29], 0
	v_mov_b64_e32 v[30:31], 0
	v_mov_b64_e32 v[32:33], 0
	v_mov_b64_e32 v[34:35], 0
	v_mov_b64_e32 v[36:37], 0
	v_mov_b64_e32 v[38:39], 0
	v_mov_b64_e32 v[40:41], 0
	v_mov_b64_e32 v[42:43], 0
	v_mov_b64_e32 v[44:45], 0
	v_mov_b64_e32 v[46:47], 0
	v_mov_b64_e32 v[48:49], 0
	v_mov_b64_e32 v[50:51], 0
	v_mov_b64_e32 v[52:53], 0
	v_mov_b64_e32 v[54:55], 0
	v_mov_b64_e32 v[56:57], 0
	v_mov_b64_e32 v[58:59], 0
	v_mov_b64_e32 v[60:61], 0
	v_mov_b64_e32 v[62:63], 0
	v_mov_b64_e32 v[64:65], 0
	v_mov_b64_e32 v[66:67], 0
	v_mov_b64_e32 v[68:69], 0
	v_mov_b64_e32 v[70:71], 0
	v_mov_b64_e32 v[72:73], 0
	v_mov_b64_e32 v[74:75], 0
	v_mov_b64_e32 v[76:77], 0
	v_mov_b64_e32 v[78:79], 0
	v_mov_b64_e32 v[80:81], 0
	v_mov_b64_e32 v[82:83], 0
	v_mov_b64_e32 v[84:85], 0
	v_mov_b64_e32 v[86:87], 0
	v_mov_b64_e32 v[88:89], 0
	v_mov_b64_e32 v[90:91], 0
	v_mov_b64_e32 v[92:93], 0
	v_mov_b64_e32 v[94:95], 0
	v_mov_b64_e32 v[96:97], 0
	v_mov_b64_e32 v[98:99], 0
	v_mov_b64_e32 v[100:101], 0
	v_mov_b64_e32 v[102:103], 0
	v_mov_b64_e32 v[104:105], 0
	v_mov_b64_e32 v[106:107], 0
	v_mov_b64_e32 v[108:109], 0
	v_mov_b64_e32 v[110:111], 0
	v_mov_b64_e32 v[112:113], 0
	v_mov_b64_e32 v[114:115], 0
	v_mov_b64_e32 v[116:117], 0
	v_mov_b64_e32 v[118:119], 0
	v_mov_b64_e32 v[120:121], 0
	v_mov_b64_e32 v[122:123], 0
	v_mov_b64_e32 v[124:125], 0
	v_mov_b64_e32 v[126:127], 0
	s_cmp_lg_u32 s98, 1
	s_cbranch_scc0 .LBB0_68
	ds_read_b128 v[128:131], v203
	ds_read_b128 v[132:135], v203 offset:1024
	ds_read_b128 v[136:139], v203 offset:2048
	ds_read_b128 v[140:143], v203 offset:3072
	ds_read_b128 v[144:147], v204
	ds_read_b128 v[148:151], v204 offset:1024
	ds_read_b128 v[180:183], v204 offset:2048
	ds_read_b128 v[184:187], v204 offset:3072
	s_add_u32 s30, s82, 0xfff80080
	s_addc_u32 s31, s83, -1
	s_cmp_eq_u32 s29, 28
	s_cselect_b32 s87, s1, s31
	s_cselect_b32 s86, s75, s30
	s_cselect_b32 s85, s73, vcc_hi
	s_cselect_b32 s84, s81, vcc_lo
	ds_read_b128 v[206:209], v205
	ds_read_b128 v[210:213], v205 offset:1024
	ds_read_b128 v[214:217], v205 offset:2048
	ds_read_b128 v[218:221], v205 offset:3072
	ds_read_b128 v[222:225], v205 offset:4096
	ds_read_b128 v[226:229], v205 offset:5120
	ds_read_b128 v[230:233], v205 offset:6144
	ds_read_b128 v[234:237], v205 offset:7168
	s_waitcnt vmcnt(16)
	s_waitcnt lgkmcnt(0)
	s_barrier
	s_setprio 1
	s_waitcnt lgkmcnt(0)
	v_mfma_f32_16x16x32_bf16 v[124:127], v[128:131], v[206:209], v[124:127]
	v_mfma_f32_16x16x32_bf16 v[120:123], v[136:139], v[206:209], v[120:123]
	v_mfma_f32_16x16x32_bf16 v[116:119], v[128:131], v[214:217], v[116:119]
	v_mfma_f32_16x16x32_bf16 v[112:115], v[136:139], v[214:217], v[112:115]
	v_mfma_f32_16x16x32_bf16 v[108:111], v[128:131], v[222:225], v[108:111]
	v_mfma_f32_16x16x32_bf16 v[104:107], v[136:139], v[222:225], v[104:107]
	v_mfma_f32_16x16x32_bf16 v[100:103], v[128:131], v[230:233], v[100:103]
	v_mfma_f32_16x16x32_bf16 v[96:99], v[136:139], v[230:233], v[96:99]
	v_mfma_f32_16x16x32_bf16 v[124:127], v[132:135], v[210:213], v[124:127]
	v_mfma_f32_16x16x32_bf16 v[120:123], v[140:143], v[210:213], v[120:123]
	v_mfma_f32_16x16x32_bf16 v[116:119], v[132:135], v[218:221], v[116:119]
	v_mfma_f32_16x16x32_bf16 v[112:115], v[140:143], v[218:221], v[112:115]
	v_mfma_f32_16x16x32_bf16 v[108:111], v[132:135], v[226:229], v[108:111]
	v_mfma_f32_16x16x32_bf16 v[104:107], v[140:143], v[226:229], v[104:107]
	v_mfma_f32_16x16x32_bf16 v[100:103], v[132:135], v[234:237], v[100:103]
	v_mfma_f32_16x16x32_bf16 v[96:99], v[140:143], v[234:237], v[96:99]
	s_setprio 0
	s_setprio 1
	v_mfma_f32_16x16x32_bf16 v[68:71], v[144:147], v[206:209], v[68:71]
	v_mfma_f32_16x16x32_bf16 v[64:67], v[180:183], v[206:209], v[64:67]
	v_mfma_f32_16x16x32_bf16 v[52:55], v[144:147], v[214:217], v[52:55]
	v_mfma_f32_16x16x32_bf16 v[48:51], v[180:183], v[214:217], v[48:51]
	v_mfma_f32_16x16x32_bf16 v[44:47], v[144:147], v[222:225], v[44:47]
	v_mfma_f32_16x16x32_bf16 v[40:43], v[180:183], v[222:225], v[40:43]
	v_mfma_f32_16x16x32_bf16 v[36:39], v[144:147], v[230:233], v[36:39]
	v_mfma_f32_16x16x32_bf16 v[32:35], v[180:183], v[230:233], v[32:35]
	v_mfma_f32_16x16x32_bf16 v[68:71], v[148:151], v[210:213], v[68:71]
	v_mfma_f32_16x16x32_bf16 v[64:67], v[184:187], v[210:213], v[64:67]
	v_mfma_f32_16x16x32_bf16 v[52:55], v[148:151], v[218:221], v[52:55]
	v_mfma_f32_16x16x32_bf16 v[48:51], v[184:187], v[218:221], v[48:51]
	v_mfma_f32_16x16x32_bf16 v[44:47], v[148:151], v[226:229], v[44:47]
	v_mfma_f32_16x16x32_bf16 v[40:43], v[184:187], v[226:229], v[40:43]
	v_mfma_f32_16x16x32_bf16 v[36:39], v[148:151], v[234:237], v[36:39]
	v_mfma_f32_16x16x32_bf16 v[32:35], v[184:187], v[234:237], v[32:35]
	s_setprio 0
	s_barrier
; #define PG8_STAGE(bufoff, gbase, voff) do { _Pragma("unroll") for (int _i = 0; _i < 2; ++_i) \
;         __builtin_amdgcn_global_load_lds((const unsigned*)((const char*)(gbase) + (voff)[_i]), (PG8_LAS unsigned*)(lds + (bufoff) + ldsw + _i * 8192), 16, 0, 0); } while (0)
; #define PG8_LDA(dst, b, h) do { _Pragma("unroll") for (int m = 0; m < 4; ++m) _Pragma("unroll") for (int k = 0; k < 2; ++k) dst[m][k] = *(const PG8_LAS bf16x8*)(lds + PG8_SA(b, h) + aoff + m * 2048 + k * 1024); } while (0)
; #define PG8_LDB(dst, b, h) do { _Pragma("unroll") for (int n = 0; n < 2; ++n) _Pragma("unroll") for (int k = 0; k < 2; ++k) dst[n][k] = *(const PG8_LAS bf16x8*)(lds + PG8_SB(b, h) + boff + n * 2048 + k * 1024); } while (0)
; #define PG8_MMA(ai, bj, At, Bt) do { __builtin_amdgcn_s_setprio(1); _Pragma("unroll") for (int m = 0; m < 4; ++m) _Pragma("unroll") for (int n = 0; n < 2; ++n) _Pragma("unroll") for (int k = 0; k < 2; ++k) \
;         acc[ai][bj][m][n] = __builtin_amdgcn_mfma_f32_16x16x32_bf16(Bt[n][k], At[m][k], acc[ai][bj][m][n], 0, 0, 0); __builtin_amdgcn_s_setprio(0); } while (0)
; #define PG8_WAIT_V(n) asm volatile("s_waitcnt vmcnt(" #n ")" ::: "memory")
; #define PG8_WAIT_L(n) asm volatile("s_waitcnt lgkmcnt(" #n ")" ::: "memory")
; #define PG8_BAR __builtin_amdgcn_s_barrier()
; #define PG8_SCHED __builtin_amdgcn_sched_barrier(0)
; template <class Epi, class Sched, bool ALIGN_EPI = false, bool SP2 = false>
; __device__ __forceinline__ void gemm_phase(PG8_LAS unsigned char* lds, const Gemm g, const Sched& S, const Epi& E) {
;     ...
;             PG8_WAIT_V(8); PG8_WAIT_L(0); PG8_BAR; PG8_MMA(0, 0, At, B0); PG8_MMA(0, 1, At, B1); PG8_BAR; PG8_SCHED;
;             PG8_LDA(At, 0, 1); PG8_STAGE(PG8_SB(0, 0), b2, voffB); PG8_STAGE(PG8_SB(0, 1), b2 + hstep, voffB); PG8_STAGE(PG8_SA(0, 0), a2, voffA);
;             PG8_WAIT_V(8); PG8_WAIT_L(0); PG8_BAR; PG8_MMA(1, 0, At, B0); PG8_MMA(1, 1, At, B1); PG8_BAR; PG8_SCHED;
;             PG8_LDB(B0, 1, 0); PG8_LDB(B1, 1, 1); PG8_SCHED; PG8_LDA(At, 1, 0); PG8_STAGE(PG8_SA(0, 1), a2 + hstep, voffA);
	s_add_i32 s30, s47, s92
	v_lshl_add_u64 v[152:153], s[84:85], 0, v[158:159]
	s_mov_b32 m0, s30
	ds_read_b128 v[206:209], v205 offset:16384
	ds_read_b128 v[210:213], v205 offset:17408
	ds_read_b128 v[214:217], v205 offset:18432
	ds_read_b128 v[218:221], v205 offset:19456
	ds_read_b128 v[222:225], v205 offset:20480
	ds_read_b128 v[226:229], v205 offset:21504
	ds_read_b128 v[230:233], v205 offset:22528
	ds_read_b128 v[234:237], v205 offset:23552
	global_load_lds_dwordx4 v[152:153], off
	s_add_i32 m0, s30, 0x2000
	s_add_u32 s30, s84, 0x80000
	v_lshl_add_u64 v[188:189], s[84:85], 0, v[154:155]
	s_addc_u32 s31, s85, 0
	s_add_i32 s89, s33, s92
	global_load_lds_dwordx4 v[188:189], off
	v_lshl_add_u64 v[238:239], s[30:31], 0, v[158:159]
	s_mov_b32 m0, s89
	v_lshl_add_u64 v[240:241], s[86:87], 0, v[156:157]
	global_load_lds_dwordx4 v[238:239], off
	v_lshl_add_u64 v[238:239], s[30:31], 0, v[154:155]
	s_add_i32 m0, s89, 0x2000
	s_nop 0
	global_load_lds_dwordx4 v[238:239], off
	v_lshl_add_u64 v[238:239], s[86:87], 0, v[160:161]
	s_mov_b32 m0, s94
	s_nop 0
	global_load_lds_dwordx4 v[238:239], off
	s_mov_b32 m0, s95
	s_nop 0
	global_load_lds_dwordx4 v[240:241], off
	s_waitcnt vmcnt(16)
	s_waitcnt lgkmcnt(0)
	s_barrier
	s_setprio 1
	s_waitcnt lgkmcnt(0)
	v_mfma_f32_16x16x32_bf16 v[92:95], v[128:131], v[206:209], v[92:95]
	v_mfma_f32_16x16x32_bf16 v[88:91], v[136:139], v[206:209], v[88:91]
	v_mfma_f32_16x16x32_bf16 v[84:87], v[128:131], v[214:217], v[84:87]
	v_mfma_f32_16x16x32_bf16 v[80:83], v[136:139], v[214:217], v[80:83]
	v_mfma_f32_16x16x32_bf16 v[76:79], v[128:131], v[222:225], v[76:79]
	v_mfma_f32_16x16x32_bf16 v[72:75], v[136:139], v[222:225], v[72:75]
	v_mfma_f32_16x16x32_bf16 v[60:63], v[128:131], v[230:233], v[60:63]
	v_mfma_f32_16x16x32_bf16 v[56:59], v[136:139], v[230:233], v[56:59]
	v_mfma_f32_16x16x32_bf16 v[92:95], v[132:135], v[210:213], v[92:95]
	v_mfma_f32_16x16x32_bf16 v[88:91], v[140:143], v[210:213], v[88:91]
	v_mfma_f32_16x16x32_bf16 v[84:87], v[132:135], v[218:221], v[84:87]
	v_mfma_f32_16x16x32_bf16 v[80:83], v[140:143], v[218:221], v[80:83]
	v_mfma_f32_16x16x32_bf16 v[76:79], v[132:135], v[226:229], v[76:79]
	v_mfma_f32_16x16x32_bf16 v[72:75], v[140:143], v[226:229], v[72:75]
	v_mfma_f32_16x16x32_bf16 v[60:63], v[132:135], v[234:237], v[60:63]
	v_mfma_f32_16x16x32_bf16 v[56:59], v[140:143], v[234:237], v[56:59]
	s_setprio 0
	s_setprio 1
	v_mfma_f32_16x16x32_bf16 v[28:31], v[144:147], v[206:209], v[28:31]
	v_mfma_f32_16x16x32_bf16 v[24:27], v[180:183], v[206:209], v[24:27]
	v_mfma_f32_16x16x32_bf16 v[20:23], v[144:147], v[214:217], v[20:23]
	v_mfma_f32_16x16x32_bf16 v[16:19], v[180:183], v[214:217], v[16:19]
	v_mfma_f32_16x16x32_bf16 v[12:15], v[144:147], v[222:225], v[12:15]
	v_mfma_f32_16x16x32_bf16 v[8:11], v[180:183], v[222:225], v[8:11]
	v_mfma_f32_16x16x32_bf16 v[4:7], v[144:147], v[230:233], v[4:7]
	v_mfma_f32_16x16x32_bf16 v[0:3], v[180:183], v[230:233], v[0:3]
	v_mfma_f32_16x16x32_bf16 v[28:31], v[148:151], v[210:213], v[28:31]
	v_mfma_f32_16x16x32_bf16 v[24:27], v[184:187], v[210:213], v[24:27]
	v_mfma_f32_16x16x32_bf16 v[20:23], v[148:151], v[218:221], v[20:23]
	v_mfma_f32_16x16x32_bf16 v[16:19], v[184:187], v[218:221], v[16:19]
	v_mfma_f32_16x16x32_bf16 v[12:15], v[148:151], v[226:229], v[12:15]
	v_mfma_f32_16x16x32_bf16 v[8:11], v[184:187], v[226:229], v[8:11]
	v_mfma_f32_16x16x32_bf16 v[4:7], v[148:151], v[234:237], v[4:7]
	v_mfma_f32_16x16x32_bf16 v[0:3], v[184:187], v[234:237], v[0:3]
	s_setprio 0
	s_barrier
	s_add_i32 s89, 0, 0x18000
	s_add_i32 s54, 0, 0x1c000
	v_add_u32_e32 v140, s89, v190
	v_add_u32_e32 v162, s54, v190
	ds_read_b128 v[128:131], v140
	ds_read_b128 v[132:135], v140 offset:1024
	ds_read_b128 v[136:139], v140 offset:2048
	ds_read_b128 v[140:143], v140 offset:3072
	ds_read_b128 v[144:147], v162
	ds_read_b128 v[148:151], v162 offset:1024
	ds_read_b128 v[180:183], v162 offset:2048
	ds_read_b128 v[184:187], v162 offset:3072
	s_add_u32 s30, s86, 0x80000
	s_addc_u32 s31, s87, 0
	s_mov_b32 m0, s96
	v_lshl_add_u64 v[242:243], s[30:31], 0, v[160:161]
	ds_read_b128 v[206:209], v205 offset:32768
	ds_read_b128 v[210:213], v205 offset:33792
	ds_read_b128 v[214:217], v205 offset:34816
	ds_read_b128 v[218:221], v205 offset:35840
	ds_read_b128 v[222:225], v205 offset:36864
	ds_read_b128 v[226:229], v205 offset:37888
	ds_read_b128 v[230:233], v205 offset:38912
	ds_read_b128 v[234:237], v205 offset:39936
	global_load_lds_dwordx4 v[242:243], off
	v_lshl_add_u64 v[242:243], s[30:31], 0, v[156:157]
	s_mov_b32 m0, s97
	s_nop 0
	global_load_lds_dwordx4 v[242:243], off
	s_waitcnt vmcnt(16)
	s_waitcnt lgkmcnt(0)
	s_barrier
; #define PG8_STAGE(bufoff, gbase, voff) do { _Pragma("unroll") for (int _i = 0; _i < 2; ++_i) \
;         __builtin_amdgcn_global_load_lds((const unsigned*)((const char*)(gbase) + (voff)[_i]), (PG8_LAS unsigned*)(lds + (bufoff) + ldsw + _i * 8192), 16, 0, 0); } while (0)
; #define PG8_LDA(dst, b, h) do { _Pragma("unroll") for (int m = 0; m < 4; ++m) _Pragma("unroll") for (int k = 0; k < 2; ++k) dst[m][k] = *(const PG8_LAS bf16x8*)(lds + PG8_SA(b, h) + aoff + m * 2048 + k * 1024); } while (0)
; #define PG8_MMA(ai, bj, At, Bt) do { __builtin_amdgcn_s_setprio(1); _Pragma("unroll") for (int m = 0; m < 4; ++m) _Pragma("unroll") for (int n = 0; n < 2; ++n) _Pragma("unroll") for (int k = 0; k < 2; ++k) \
;         acc[ai][bj][m][n] = __builtin_amdgcn_mfma_f32_16x16x32_bf16(Bt[n][k], At[m][k], acc[ai][bj][m][n], 0, 0, 0); __builtin_amdgcn_s_setprio(0); } while (0)
; #define PG8_WAIT_V(n) asm volatile("s_waitcnt vmcnt(" #n ")" ::: "memory")
; #define PG8_WAIT_L(n) asm volatile("s_waitcnt lgkmcnt(" #n ")" ::: "memory")
; #define PG8_BAR __builtin_amdgcn_s_barrier()
; #define PG8_SCHED __builtin_amdgcn_sched_barrier(0)
; template <class Epi, class Sched, bool ALIGN_EPI = false, bool SP2 = false>
; __device__ __forceinline__ void gemm_phase(PG8_LAS unsigned char* lds, const Gemm g, const Sched& S, const Epi& E) {
;     ...
;             PG8_WAIT_V(8); PG8_WAIT_L(0); PG8_BAR; PG8_MMA(0, 0, At, B0); PG8_MMA(0, 1, At, B1); PG8_BAR; PG8_SCHED;
;             PG8_LDA(At, 1, 1); PG8_STAGE(PG8_SB(1, 0), b3, voffB); PG8_STAGE(PG8_SB(1, 1), b3 + hstep, voffB); PG8_STAGE(PG8_SA(1, 0), a3, voffA);
;             PG8_WAIT_V(8); PG8_WAIT_L(0); PG8_BAR; PG8_MMA(1, 0, At, B0); PG8_MMA(1, 1, At, B1); PG8_BAR; PG8_SCHED;
	s_setprio 1
	s_waitcnt lgkmcnt(0)
	v_mfma_f32_16x16x32_bf16 v[124:127], v[128:131], v[206:209], v[124:127]
	v_mfma_f32_16x16x32_bf16 v[120:123], v[136:139], v[206:209], v[120:123]
	v_mfma_f32_16x16x32_bf16 v[116:119], v[128:131], v[214:217], v[116:119]
	v_mfma_f32_16x16x32_bf16 v[112:115], v[136:139], v[214:217], v[112:115]
	v_mfma_f32_16x16x32_bf16 v[108:111], v[128:131], v[222:225], v[108:111]
	v_mfma_f32_16x16x32_bf16 v[104:107], v[136:139], v[222:225], v[104:107]
	v_mfma_f32_16x16x32_bf16 v[100:103], v[128:131], v[230:233], v[100:103]
	v_mfma_f32_16x16x32_bf16 v[96:99], v[136:139], v[230:233], v[96:99]
	v_mfma_f32_16x16x32_bf16 v[124:127], v[132:135], v[210:213], v[124:127]
	v_mfma_f32_16x16x32_bf16 v[120:123], v[140:143], v[210:213], v[120:123]
	v_mfma_f32_16x16x32_bf16 v[116:119], v[132:135], v[218:221], v[116:119]
	v_mfma_f32_16x16x32_bf16 v[112:115], v[140:143], v[218:221], v[112:115]
	v_mfma_f32_16x16x32_bf16 v[108:111], v[132:135], v[226:229], v[108:111]
	v_mfma_f32_16x16x32_bf16 v[104:107], v[140:143], v[226:229], v[104:107]
	v_mfma_f32_16x16x32_bf16 v[100:103], v[132:135], v[234:237], v[100:103]
	v_mfma_f32_16x16x32_bf16 v[96:99], v[140:143], v[234:237], v[96:99]
	s_setprio 0
	s_setprio 1
	v_mfma_f32_16x16x32_bf16 v[68:71], v[144:147], v[206:209], v[68:71]
	v_mfma_f32_16x16x32_bf16 v[64:67], v[180:183], v[206:209], v[64:67]
	v_mfma_f32_16x16x32_bf16 v[52:55], v[144:147], v[214:217], v[52:55]
	v_mfma_f32_16x16x32_bf16 v[48:51], v[180:183], v[214:217], v[48:51]
	v_mfma_f32_16x16x32_bf16 v[44:47], v[144:147], v[222:225], v[44:47]
	v_mfma_f32_16x16x32_bf16 v[40:43], v[180:183], v[222:225], v[40:43]
	v_mfma_f32_16x16x32_bf16 v[36:39], v[144:147], v[230:233], v[36:39]
	v_mfma_f32_16x16x32_bf16 v[32:35], v[180:183], v[230:233], v[32:35]
	v_mfma_f32_16x16x32_bf16 v[68:71], v[148:151], v[210:213], v[68:71]
	v_mfma_f32_16x16x32_bf16 v[64:67], v[184:187], v[210:213], v[64:67]
	v_mfma_f32_16x16x32_bf16 v[52:55], v[148:151], v[218:221], v[52:55]
	v_mfma_f32_16x16x32_bf16 v[48:51], v[184:187], v[218:221], v[48:51]
	v_mfma_f32_16x16x32_bf16 v[44:47], v[148:151], v[226:229], v[44:47]
	v_mfma_f32_16x16x32_bf16 v[40:43], v[184:187], v[226:229], v[40:43]
	v_mfma_f32_16x16x32_bf16 v[36:39], v[148:151], v[234:237], v[36:39]
	v_mfma_f32_16x16x32_bf16 v[32:35], v[184:187], v[234:237], v[32:35]
	s_setprio 0
	s_barrier
	s_add_i32 s30, s89, s92
	v_lshl_add_u64 v[152:153], v[152:153], 0, s[62:63]
	s_mov_b32 m0, s30
	ds_read_b128 v[206:209], v205 offset:49152
	ds_read_b128 v[210:213], v205 offset:50176
	ds_read_b128 v[214:217], v205 offset:51200
	ds_read_b128 v[218:221], v205 offset:52224
	ds_read_b128 v[222:225], v205 offset:53248
	ds_read_b128 v[226:229], v205 offset:54272
	ds_read_b128 v[230:233], v205 offset:55296
	ds_read_b128 v[234:237], v205 offset:56320
	global_load_lds_dwordx4 v[152:153], off
	s_add_i32 m0, s30, 0x2000
	s_add_u32 s30, s84, 0x80080
	v_lshl_add_u64 v[152:153], v[188:189], 0, s[62:63]
	s_addc_u32 s31, s85, 0
	s_add_i32 s54, s54, s92
	global_load_lds_dwordx4 v[152:153], off
	v_lshl_add_u64 v[152:153], s[30:31], 0, v[158:159]
	s_mov_b32 m0, s54
	s_nop 0
	global_load_lds_dwordx4 v[152:153], off
	v_lshl_add_u64 v[152:153], s[30:31], 0, v[154:155]
	s_add_i32 m0, s54, 0x2000
	s_nop 0
	global_load_lds_dwordx4 v[152:153], off
	v_lshl_add_u64 v[152:153], v[238:239], 0, s[62:63]
	s_mov_b32 m0, s88
	s_nop 0
	global_load_lds_dwordx4 v[152:153], off
	v_lshl_add_u64 v[152:153], v[240:241], 0, s[62:63]
	s_mov_b32 m0, s46
	s_nop 0
	global_load_lds_dwordx4 v[152:153], off
	s_waitcnt vmcnt(8)
	s_waitcnt lgkmcnt(0)
	s_barrier
	s_setprio 1
	s_waitcnt lgkmcnt(0)
	v_mfma_f32_16x16x32_bf16 v[92:95], v[128:131], v[206:209], v[92:95]
	v_mfma_f32_16x16x32_bf16 v[88:91], v[136:139], v[206:209], v[88:91]
	v_mfma_f32_16x16x32_bf16 v[84:87], v[128:131], v[214:217], v[84:87]
	v_mfma_f32_16x16x32_bf16 v[80:83], v[136:139], v[214:217], v[80:83]
	v_mfma_f32_16x16x32_bf16 v[76:79], v[128:131], v[222:225], v[76:79]
	v_mfma_f32_16x16x32_bf16 v[72:75], v[136:139], v[222:225], v[72:75]
	v_mfma_f32_16x16x32_bf16 v[60:63], v[128:131], v[230:233], v[60:63]
	v_mfma_f32_16x16x32_bf16 v[56:59], v[136:139], v[230:233], v[56:59]
	v_mfma_f32_16x16x32_bf16 v[92:95], v[132:135], v[210:213], v[92:95]
	v_mfma_f32_16x16x32_bf16 v[88:91], v[140:143], v[210:213], v[88:91]
	v_mfma_f32_16x16x32_bf16 v[84:87], v[132:135], v[218:221], v[84:87]
	v_mfma_f32_16x16x32_bf16 v[80:83], v[140:143], v[218:221], v[80:83]
	v_mfma_f32_16x16x32_bf16 v[76:79], v[132:135], v[226:229], v[76:79]
	v_mfma_f32_16x16x32_bf16 v[72:75], v[140:143], v[226:229], v[72:75]
	v_mfma_f32_16x16x32_bf16 v[60:63], v[132:135], v[234:237], v[60:63]
	v_mfma_f32_16x16x32_bf16 v[56:59], v[140:143], v[234:237], v[56:59]
	s_setprio 0
	s_setprio 1
	v_mfma_f32_16x16x32_bf16 v[28:31], v[144:147], v[206:209], v[28:31]
	v_mfma_f32_16x16x32_bf16 v[24:27], v[180:183], v[206:209], v[24:27]
	v_mfma_f32_16x16x32_bf16 v[20:23], v[144:147], v[214:217], v[20:23]
	v_mfma_f32_16x16x32_bf16 v[16:19], v[180:183], v[214:217], v[16:19]
	v_mfma_f32_16x16x32_bf16 v[12:15], v[144:147], v[222:225], v[12:15]
	v_mfma_f32_16x16x32_bf16 v[8:11], v[180:183], v[222:225], v[8:11]
	v_mfma_f32_16x16x32_bf16 v[4:7], v[144:147], v[230:233], v[4:7]
	v_mfma_f32_16x16x32_bf16 v[0:3], v[180:183], v[230:233], v[0:3]
	v_mfma_f32_16x16x32_bf16 v[28:31], v[148:151], v[210:213], v[28:31]
	v_mfma_f32_16x16x32_bf16 v[24:27], v[184:187], v[210:213], v[24:27]
	v_mfma_f32_16x16x32_bf16 v[20:23], v[148:151], v[218:221], v[20:23]
	v_mfma_f32_16x16x32_bf16 v[16:19], v[184:187], v[218:221], v[16:19]
	v_mfma_f32_16x16x32_bf16 v[12:15], v[148:151], v[226:229], v[12:15]
	v_mfma_f32_16x16x32_bf16 v[8:11], v[184:187], v[226:229], v[8:11]
	v_mfma_f32_16x16x32_bf16 v[4:7], v[148:151], v[234:237], v[4:7]
	v_mfma_f32_16x16x32_bf16 v[0:3], v[184:187], v[234:237], v[0:3]
	s_setprio 0
	s_barrier
	s_add_i32 s29, s29, 2
	s_add_u32 s82, s82, 0x100
	s_addc_u32 s83, s83, 0
	s_add_u32 vcc_lo, vcc_lo, 0x100
	s_addc_u32 vcc_hi, vcc_hi, 0
; #define PG8_STAGE(bufoff, gbase, voff) do { _Pragma("unroll") for (int _i = 0; _i < 2; ++_i) \
;         __builtin_amdgcn_global_load_lds((const unsigned*)((const char*)(gbase) + (voff)[_i]), (PG8_LAS unsigned*)(lds + (bufoff) + ldsw + _i * 8192), 16, 0, 0); } while (0)
; #define PG8_LDA(dst, b, h) do { _Pragma("unroll") for (int m = 0; m < 4; ++m) _Pragma("unroll") for (int k = 0; k < 2; ++k) dst[m][k] = *(const PG8_LAS bf16x8*)(lds + PG8_SA(b, h) + aoff + m * 2048 + k * 1024); } while (0)
; #define PG8_LDB(dst, b, h) do { _Pragma("unroll") for (int n = 0; n < 2; ++n) _Pragma("unroll") for (int k = 0; k < 2; ++k) dst[n][k] = *(const PG8_LAS bf16x8*)(lds + PG8_SB(b, h) + boff + n * 2048 + k * 1024); } while (0)
; #define PG8_MMA(ai, bj, At, Bt) do { __builtin_amdgcn_s_setprio(1); _Pragma("unroll") for (int m = 0; m < 4; ++m) _Pragma("unroll") for (int n = 0; n < 2; ++n) _Pragma("unroll") for (int k = 0; k < 2; ++k) \
;         acc[ai][bj][m][n] = __builtin_amdgcn_mfma_f32_16x16x32_bf16(Bt[n][k], At[m][k], acc[ai][bj][m][n], 0, 0, 0); __builtin_amdgcn_s_setprio(0); } while (0)
; #define PG8_WAIT_V(n) asm volatile("s_waitcnt vmcnt(" #n ")" ::: "memory")
; #define PG8_WAIT_L(n) asm volatile("s_waitcnt lgkmcnt(" #n ")" ::: "memory")
; #define PG8_BAR __builtin_amdgcn_s_barrier()
; #define PG8_SCHED __builtin_amdgcn_sched_barrier(0)
; template <class Epi, class Sched, bool ALIGN_EPI = false, bool SP2 = false>
; __device__ __forceinline__ void gemm_phase(PG8_LAS unsigned char* lds, const Gemm g, const Sched& S, const Epi& E) {
;     ...
;             if constexpr (SP2) {
;             PG8_LDB(B0, 0, 0); PG8_LDB(B1, 0, 1); PG8_SCHED; PG8_LDA(At, 0, 0); PG8_STAGE(PG8_SA(1, 1), a1 + hstep, voffA);
;             PG8_WAIT_V(8); PG8_WAIT_L(0); PG8_BAR; PG8_MMA(0, 0, At, B0); PG8_MMA(0, 1, At, B1); PG8_BAR; PG8_SCHED;
;             PG8_LDA(At, 0, 1); PG8_STAGE(PG8_SB(0, 0), b2, voffB); PG8_STAGE(PG8_SB(0, 1), b2 + hstep, voffB); PG8_STAGE(PG8_SA(0, 0), a2, voffA);
.LBB0_68:
	ds_read_b128 v[128:131], v203
	ds_read_b128 v[132:135], v203 offset:1024
	ds_read_b128 v[136:139], v203 offset:2048
	ds_read_b128 v[140:143], v203 offset:3072
	ds_read_b128 v[144:147], v204
	ds_read_b128 v[148:151], v204 offset:1024
	ds_read_b128 v[180:183], v204 offset:2048
	ds_read_b128 v[184:187], v204 offset:3072
	s_add_u32 s30, s82, 0xfff80080
	s_addc_u32 s31, s83, -1
	s_cmp_eq_u32 s29, 28
	s_cselect_b32 s87, s1, s31
	s_cselect_b32 s86, s75, s30
	s_cselect_b32 s85, s73, vcc_hi
	s_cselect_b32 s84, s81, vcc_lo
	v_lshl_add_u64 v[152:153], s[82:83], 0, v[170:171]
	s_add_i32 m0, s94, 0xc000
	ds_read_b128 v[206:209], v205
	ds_read_b128 v[210:213], v205 offset:1024
	ds_read_b128 v[214:217], v205 offset:2048
	ds_read_b128 v[218:221], v205 offset:3072
	ds_read_b128 v[222:225], v205 offset:4096
	ds_read_b128 v[226:229], v205 offset:5120
	ds_read_b128 v[230:233], v205 offset:6144
	ds_read_b128 v[234:237], v205 offset:7168
	global_load_lds_dwordx4 v[152:153], off
	v_lshl_add_u64 v[152:153], s[82:83], 0, v[172:173]
	s_add_i32 m0, s94, 0xe000
	s_nop 0
	global_load_lds_dwordx4 v[152:153], off
	s_waitcnt vmcnt(8)
	s_waitcnt lgkmcnt(0)
	s_barrier
	s_setprio 1
	s_waitcnt lgkmcnt(0)
	v_mfma_f32_16x16x32_bf16 v[124:127], v[128:131], v[206:209], v[124:127]
	v_mfma_f32_16x16x32_bf16 v[120:123], v[136:139], v[206:209], v[120:123]
	v_mfma_f32_16x16x32_bf16 v[116:119], v[128:131], v[214:217], v[116:119]
	v_mfma_f32_16x16x32_bf16 v[112:115], v[136:139], v[214:217], v[112:115]
	v_mfma_f32_16x16x32_bf16 v[108:111], v[128:131], v[222:225], v[108:111]
	v_mfma_f32_16x16x32_bf16 v[104:107], v[136:139], v[222:225], v[104:107]
	v_mfma_f32_16x16x32_bf16 v[100:103], v[128:131], v[230:233], v[100:103]
	v_mfma_f32_16x16x32_bf16 v[96:99], v[136:139], v[230:233], v[96:99]
	v_mfma_f32_16x16x32_bf16 v[124:127], v[132:135], v[210:213], v[124:127]
	v_mfma_f32_16x16x32_bf16 v[120:123], v[140:143], v[210:213], v[120:123]
	v_mfma_f32_16x16x32_bf16 v[116:119], v[132:135], v[218:221], v[116:119]
	v_mfma_f32_16x16x32_bf16 v[112:115], v[140:143], v[218:221], v[112:115]
	v_mfma_f32_16x16x32_bf16 v[108:111], v[132:135], v[226:229], v[108:111]
	v_mfma_f32_16x16x32_bf16 v[104:107], v[140:143], v[226:229], v[104:107]
	v_mfma_f32_16x16x32_bf16 v[100:103], v[132:135], v[234:237], v[100:103]
	v_mfma_f32_16x16x32_bf16 v[96:99], v[140:143], v[234:237], v[96:99]
	s_setprio 0
	s_setprio 1
	v_mfma_f32_16x16x32_bf16 v[68:71], v[144:147], v[206:209], v[68:71]
	v_mfma_f32_16x16x32_bf16 v[64:67], v[180:183], v[206:209], v[64:67]
	v_mfma_f32_16x16x32_bf16 v[52:55], v[144:147], v[214:217], v[52:55]
	v_mfma_f32_16x16x32_bf16 v[48:51], v[180:183], v[214:217], v[48:51]
	v_mfma_f32_16x16x32_bf16 v[44:47], v[144:147], v[222:225], v[44:47]
	v_mfma_f32_16x16x32_bf16 v[40:43], v[180:183], v[222:225], v[40:43]
	v_mfma_f32_16x16x32_bf16 v[36:39], v[144:147], v[230:233], v[36:39]
	v_mfma_f32_16x16x32_bf16 v[32:35], v[180:183], v[230:233], v[32:35]
	v_mfma_f32_16x16x32_bf16 v[68:71], v[148:151], v[210:213], v[68:71]
	v_mfma_f32_16x16x32_bf16 v[64:67], v[184:187], v[210:213], v[64:67]
	v_mfma_f32_16x16x32_bf16 v[52:55], v[148:151], v[218:221], v[52:55]
	v_mfma_f32_16x16x32_bf16 v[48:51], v[184:187], v[218:221], v[48:51]
	v_mfma_f32_16x16x32_bf16 v[44:47], v[148:151], v[226:229], v[44:47]
	v_mfma_f32_16x16x32_bf16 v[40:43], v[184:187], v[226:229], v[40:43]
	v_mfma_f32_16x16x32_bf16 v[36:39], v[148:151], v[234:237], v[36:39]
	v_mfma_f32_16x16x32_bf16 v[32:35], v[184:187], v[234:237], v[32:35]
	s_setprio 0
	s_barrier
	s_add_i32 s30, s47, s92
	v_lshl_add_u64 v[152:153], s[84:85], 0, v[158:159]
	s_mov_b32 m0, s30
	ds_read_b128 v[206:209], v205 offset:16384
	ds_read_b128 v[210:213], v205 offset:17408
	ds_read_b128 v[214:217], v205 offset:18432
	ds_read_b128 v[218:221], v205 offset:19456
	ds_read_b128 v[222:225], v205 offset:20480
	ds_read_b128 v[226:229], v205 offset:21504
	ds_read_b128 v[230:233], v205 offset:22528
	ds_read_b128 v[234:237], v205 offset:23552
	global_load_lds_dwordx4 v[152:153], off
	s_add_i32 m0, s30, 0x2000
	s_add_u32 s30, s84, 0x80000
	v_lshl_add_u64 v[188:189], s[84:85], 0, v[154:155]
	s_addc_u32 s31, s85, 0
	s_add_i32 s89, s33, s92
	global_load_lds_dwordx4 v[188:189], off
	v_lshl_add_u64 v[238:239], s[30:31], 0, v[158:159]
	s_mov_b32 m0, s89
	v_lshl_add_u64 v[240:241], s[86:87], 0, v[156:157]
	global_load_lds_dwordx4 v[238:239], off
	v_lshl_add_u64 v[238:239], s[30:31], 0, v[154:155]
	s_add_i32 m0, s89, 0x2000
	s_nop 0
	global_load_lds_dwordx4 v[238:239], off
	v_lshl_add_u64 v[238:239], s[86:87], 0, v[160:161]
	s_mov_b32 m0, s94
	s_nop 0
	global_load_lds_dwordx4 v[238:239], off
	s_mov_b32 m0, s95
	s_nop 0
	global_load_lds_dwordx4 v[240:241], off
	s_waitcnt vmcnt(8)
	s_waitcnt lgkmcnt(0)
	s_barrier
; #define PG8_STAGE(bufoff, gbase, voff) do { _Pragma("unroll") for (int _i = 0; _i < 2; ++_i) \
;         __builtin_amdgcn_global_load_lds((const unsigned*)((const char*)(gbase) + (voff)[_i]), (PG8_LAS unsigned*)(lds + (bufoff) + ldsw + _i * 8192), 16, 0, 0); } while (0)
; #define PG8_LDA(dst, b, h) do { _Pragma("unroll") for (int m = 0; m < 4; ++m) _Pragma("unroll") for (int k = 0; k < 2; ++k) dst[m][k] = *(const PG8_LAS bf16x8*)(lds + PG8_SA(b, h) + aoff + m * 2048 + k * 1024); } while (0)
; #define PG8_LDB(dst, b, h) do { _Pragma("unroll") for (int n = 0; n < 2; ++n) _Pragma("unroll") for (int k = 0; k < 2; ++k) dst[n][k] = *(const PG8_LAS bf16x8*)(lds + PG8_SB(b, h) + boff + n * 2048 + k * 1024); } while (0)
; #define PG8_MMA(ai, bj, At, Bt) do { __builtin_amdgcn_s_setprio(1); _Pragma("unroll") for (int m = 0; m < 4; ++m) _Pragma("unroll") for (int n = 0; n < 2; ++n) _Pragma("unroll") for (int k = 0; k < 2; ++k) \
;         acc[ai][bj][m][n] = __builtin_amdgcn_mfma_f32_16x16x32_bf16(Bt[n][k], At[m][k], acc[ai][bj][m][n], 0, 0, 0); __builtin_amdgcn_s_setprio(0); } while (0)
; #define PG8_WAIT_V(n) asm volatile("s_waitcnt vmcnt(" #n ")" ::: "memory")
; #define PG8_WAIT_L(n) asm volatile("s_waitcnt lgkmcnt(" #n ")" ::: "memory")
; #define PG8_BAR __builtin_amdgcn_s_barrier()
; #define PG8_SCHED __builtin_amdgcn_sched_barrier(0)
; template <class Epi, class Sched, bool ALIGN_EPI = false, bool SP2 = false>
; __device__ __forceinline__ void gemm_phase(PG8_LAS unsigned char* lds, const Gemm g, const Sched& S, const Epi& E) {
;     ...
;             PG8_WAIT_V(8); PG8_WAIT_L(0); PG8_BAR; PG8_MMA(1, 0, At, B0); PG8_MMA(1, 1, At, B1); PG8_BAR; PG8_SCHED;
;             PG8_LDB(B0, 1, 0); PG8_LDB(B1, 1, 1); PG8_SCHED; PG8_LDA(At, 1, 0); PG8_STAGE(PG8_SA(0, 1), a2 + hstep, voffA);
;             PG8_WAIT_V(8); PG8_WAIT_L(0); PG8_BAR; PG8_MMA(0, 0, At, B0); PG8_MMA(0, 1, At, B1); PG8_BAR; PG8_SCHED;
	s_setprio 1
	s_waitcnt lgkmcnt(0)
	v_mfma_f32_16x16x32_bf16 v[92:95], v[128:131], v[206:209], v[92:95]
	v_mfma_f32_16x16x32_bf16 v[88:91], v[136:139], v[206:209], v[88:91]
	v_mfma_f32_16x16x32_bf16 v[84:87], v[128:131], v[214:217], v[84:87]
	v_mfma_f32_16x16x32_bf16 v[80:83], v[136:139], v[214:217], v[80:83]
	v_mfma_f32_16x16x32_bf16 v[76:79], v[128:131], v[222:225], v[76:79]
	v_mfma_f32_16x16x32_bf16 v[72:75], v[136:139], v[222:225], v[72:75]
	v_mfma_f32_16x16x32_bf16 v[60:63], v[128:131], v[230:233], v[60:63]
	v_mfma_f32_16x16x32_bf16 v[56:59], v[136:139], v[230:233], v[56:59]
	v_mfma_f32_16x16x32_bf16 v[92:95], v[132:135], v[210:213], v[92:95]
	v_mfma_f32_16x16x32_bf16 v[88:91], v[140:143], v[210:213], v[88:91]
	v_mfma_f32_16x16x32_bf16 v[84:87], v[132:135], v[218:221], v[84:87]
	v_mfma_f32_16x16x32_bf16 v[80:83], v[140:143], v[218:221], v[80:83]
	v_mfma_f32_16x16x32_bf16 v[76:79], v[132:135], v[226:229], v[76:79]
	v_mfma_f32_16x16x32_bf16 v[72:75], v[140:143], v[226:229], v[72:75]
	v_mfma_f32_16x16x32_bf16 v[60:63], v[132:135], v[234:237], v[60:63]
	v_mfma_f32_16x16x32_bf16 v[56:59], v[140:143], v[234:237], v[56:59]
	s_setprio 0
	s_setprio 1
	v_mfma_f32_16x16x32_bf16 v[28:31], v[144:147], v[206:209], v[28:31]
	v_mfma_f32_16x16x32_bf16 v[24:27], v[180:183], v[206:209], v[24:27]
	v_mfma_f32_16x16x32_bf16 v[20:23], v[144:147], v[214:217], v[20:23]
	v_mfma_f32_16x16x32_bf16 v[16:19], v[180:183], v[214:217], v[16:19]
	v_mfma_f32_16x16x32_bf16 v[12:15], v[144:147], v[222:225], v[12:15]
	v_mfma_f32_16x16x32_bf16 v[8:11], v[180:183], v[222:225], v[8:11]
	v_mfma_f32_16x16x32_bf16 v[4:7], v[144:147], v[230:233], v[4:7]
	v_mfma_f32_16x16x32_bf16 v[0:3], v[180:183], v[230:233], v[0:3]
	v_mfma_f32_16x16x32_bf16 v[28:31], v[148:151], v[210:213], v[28:31]
	v_mfma_f32_16x16x32_bf16 v[24:27], v[184:187], v[210:213], v[24:27]
	v_mfma_f32_16x16x32_bf16 v[20:23], v[148:151], v[218:221], v[20:23]
	v_mfma_f32_16x16x32_bf16 v[16:19], v[184:187], v[218:221], v[16:19]
	v_mfma_f32_16x16x32_bf16 v[12:15], v[148:151], v[226:229], v[12:15]
	v_mfma_f32_16x16x32_bf16 v[8:11], v[184:187], v[226:229], v[8:11]
	v_mfma_f32_16x16x32_bf16 v[4:7], v[148:151], v[234:237], v[4:7]
	v_mfma_f32_16x16x32_bf16 v[0:3], v[184:187], v[234:237], v[0:3]
	s_setprio 0
	s_barrier
	s_add_i32 s89, 0, 0x18000
	s_add_i32 s54, 0, 0x1c000
	v_add_u32_e32 v140, s89, v190
	v_add_u32_e32 v162, s54, v190
	ds_read_b128 v[128:131], v140
	ds_read_b128 v[132:135], v140 offset:1024
	ds_read_b128 v[136:139], v140 offset:2048
	ds_read_b128 v[140:143], v140 offset:3072
	ds_read_b128 v[144:147], v162
	ds_read_b128 v[148:151], v162 offset:1024
	ds_read_b128 v[180:183], v162 offset:2048
	ds_read_b128 v[184:187], v162 offset:3072
	s_add_u32 s30, s86, 0x80000
	s_addc_u32 s31, s87, 0
	s_mov_b32 m0, s96
	v_lshl_add_u64 v[242:243], s[30:31], 0, v[160:161]
	ds_read_b128 v[206:209], v205 offset:32768
	ds_read_b128 v[210:213], v205 offset:33792
	ds_read_b128 v[214:217], v205 offset:34816
	ds_read_b128 v[218:221], v205 offset:35840
	ds_read_b128 v[222:225], v205 offset:36864
	ds_read_b128 v[226:229], v205 offset:37888
	ds_read_b128 v[230:233], v205 offset:38912
	ds_read_b128 v[234:237], v205 offset:39936
	global_load_lds_dwordx4 v[242:243], off
	v_lshl_add_u64 v[242:243], s[30:31], 0, v[156:157]
	s_mov_b32 m0, s97
	s_nop 0
	global_load_lds_dwordx4 v[242:243], off
	s_waitcnt vmcnt(8)
	s_waitcnt lgkmcnt(0)
	s_barrier
	s_setprio 1
	s_waitcnt lgkmcnt(0)
	v_mfma_f32_16x16x32_bf16 v[124:127], v[128:131], v[206:209], v[124:127]
	v_mfma_f32_16x16x32_bf16 v[120:123], v[136:139], v[206:209], v[120:123]
	v_mfma_f32_16x16x32_bf16 v[116:119], v[128:131], v[214:217], v[116:119]
	v_mfma_f32_16x16x32_bf16 v[112:115], v[136:139], v[214:217], v[112:115]
	v_mfma_f32_16x16x32_bf16 v[108:111], v[128:131], v[222:225], v[108:111]
	v_mfma_f32_16x16x32_bf16 v[104:107], v[136:139], v[222:225], v[104:107]
	v_mfma_f32_16x16x32_bf16 v[100:103], v[128:131], v[230:233], v[100:103]
	v_mfma_f32_16x16x32_bf16 v[96:99], v[136:139], v[230:233], v[96:99]
	v_mfma_f32_16x16x32_bf16 v[124:127], v[132:135], v[210:213], v[124:127]
	v_mfma_f32_16x16x32_bf16 v[120:123], v[140:143], v[210:213], v[120:123]
	v_mfma_f32_16x16x32_bf16 v[116:119], v[132:135], v[218:221], v[116:119]
	v_mfma_f32_16x16x32_bf16 v[112:115], v[140:143], v[218:221], v[112:115]
	v_mfma_f32_16x16x32_bf16 v[108:111], v[132:135], v[226:229], v[108:111]
	v_mfma_f32_16x16x32_bf16 v[104:107], v[140:143], v[226:229], v[104:107]
	v_mfma_f32_16x16x32_bf16 v[100:103], v[132:135], v[234:237], v[100:103]
	v_mfma_f32_16x16x32_bf16 v[96:99], v[140:143], v[234:237], v[96:99]
	s_setprio 0
	s_setprio 1
	v_mfma_f32_16x16x32_bf16 v[68:71], v[144:147], v[206:209], v[68:71]
	v_mfma_f32_16x16x32_bf16 v[64:67], v[180:183], v[206:209], v[64:67]
	v_mfma_f32_16x16x32_bf16 v[52:55], v[144:147], v[214:217], v[52:55]
	v_mfma_f32_16x16x32_bf16 v[48:51], v[180:183], v[214:217], v[48:51]
	v_mfma_f32_16x16x32_bf16 v[44:47], v[144:147], v[222:225], v[44:47]
	v_mfma_f32_16x16x32_bf16 v[40:43], v[180:183], v[222:225], v[40:43]
	v_mfma_f32_16x16x32_bf16 v[36:39], v[144:147], v[230:233], v[36:39]
	v_mfma_f32_16x16x32_bf16 v[32:35], v[180:183], v[230:233], v[32:35]
	v_mfma_f32_16x16x32_bf16 v[68:71], v[148:151], v[210:213], v[68:71]
	v_mfma_f32_16x16x32_bf16 v[64:67], v[184:187], v[210:213], v[64:67]
	v_mfma_f32_16x16x32_bf16 v[52:55], v[148:151], v[218:221], v[52:55]
	v_mfma_f32_16x16x32_bf16 v[48:51], v[184:187], v[218:221], v[48:51]
	v_mfma_f32_16x16x32_bf16 v[44:47], v[148:151], v[226:229], v[44:47]
	v_mfma_f32_16x16x32_bf16 v[40:43], v[184:187], v[226:229], v[40:43]
	v_mfma_f32_16x16x32_bf16 v[36:39], v[148:151], v[234:237], v[36:39]
	v_mfma_f32_16x16x32_bf16 v[32:35], v[184:187], v[234:237], v[32:35]
	s_setprio 0
	s_barrier
; #define PG8_STAGE(bufoff, gbase, voff) do { _Pragma("unroll") for (int _i = 0; _i < 2; ++_i) \
;         __builtin_amdgcn_global_load_lds((const unsigned*)((const char*)(gbase) + (voff)[_i]), (PG8_LAS unsigned*)(lds + (bufoff) + ldsw + _i * 8192), 16, 0, 0); } while (0)
; #define PG8_LDA(dst, b, h) do { _Pragma("unroll") for (int m = 0; m < 4; ++m) _Pragma("unroll") for (int k = 0; k < 2; ++k) dst[m][k] = *(const PG8_LAS bf16x8*)(lds + PG8_SA(b, h) + aoff + m * 2048 + k * 1024); } while (0)
; #define PG8_LDB(dst, b, h) do { _Pragma("unroll") for (int n = 0; n < 2; ++n) _Pragma("unroll") for (int k = 0; k < 2; ++k) dst[n][k] = *(const PG8_LAS bf16x8*)(lds + PG8_SB(b, h) + boff + n * 2048 + k * 1024); } while (0)
; #define PG8_MMA(ai, bj, At, Bt) do { __builtin_amdgcn_s_setprio(1); _Pragma("unroll") for (int m = 0; m < 4; ++m) _Pragma("unroll") for (int n = 0; n < 2; ++n) _Pragma("unroll") for (int k = 0; k < 2; ++k) \
;         acc[ai][bj][m][n] = __builtin_amdgcn_mfma_f32_16x16x32_bf16(Bt[n][k], At[m][k], acc[ai][bj][m][n], 0, 0, 0); __builtin_amdgcn_s_setprio(0); } while (0)
; #define PG8_WAIT_V(n) asm volatile("s_waitcnt vmcnt(" #n ")" ::: "memory")
; template <class Epi, class Sched, bool ALIGN_EPI = false, bool SP2 = false>
; __device__ __forceinline__ void gemm_phase(PG8_LAS unsigned char* lds, const Gemm g, const Sched& S, const Epi& E) {
;     ...
;             PG8_LDB(B0, 0, 0); PG8_LDB(B1, 0, 1); PG8_SCHED; PG8_LDA(At, 0, 0); PG8_STAGE(PG8_SA(1, 1), a1 + hstep, voffA);
;             PG8_WAIT_V(8); PG8_WAIT_L(0); PG8_BAR; PG8_MMA(0, 0, At, B0); PG8_MMA(0, 1, At, B1); PG8_BAR; PG8_SCHED;
;             PG8_LDA(At, 0, 1); PG8_STAGE(PG8_SB(0, 0), b2, voffB); PG8_STAGE(PG8_SB(0, 1), b2 + hstep, voffB); PG8_STAGE(PG8_SA(0, 0), a2, voffA);
;             PG8_WAIT_V(8); PG8_WAIT_L(0); PG8_BAR; PG8_MMA(1, 0, At, B0); PG8_MMA(1, 1, At, B1); PG8_BAR; PG8_SCHED;
;             PG8_LDB(B0, 1, 0); PG8_LDB(B1, 1, 1); PG8_SCHED; PG8_LDA(At, 1, 0); PG8_STAGE(PG8_SA(0, 1), a2 + hstep, voffA);
;             PG8_WAIT_V(8); PG8_WAIT_L(0); PG8_BAR; PG8_MMA(0, 0, At, B0); PG8_MMA(0, 1, At, B1); PG8_BAR; PG8_SCHED;
;             PG8_LDA(At, 1, 1); PG8_STAGE(PG8_SB(1, 0), b3, voffB); PG8_STAGE(PG8_SB(1, 1), b3 + hstep, voffB); PG8_STAGE(PG8_SA(1, 0), a3, voffA);
;             PG8_WAIT_V(8); PG8_WAIT_L(0); PG8_BAR; PG8_MMA(1, 0, At, B0); PG8_MMA(1, 1, At, B1); PG8_BAR; PG8_SCHED;
	s_add_i32 s30, s89, s92
	v_lshl_add_u64 v[152:153], v[152:153], 0, s[62:63]
	s_mov_b32 m0, s30
	ds_read_b128 v[206:209], v205 offset:49152
	ds_read_b128 v[210:213], v205 offset:50176
	ds_read_b128 v[214:217], v205 offset:51200
	ds_read_b128 v[218:221], v205 offset:52224
	ds_read_b128 v[222:225], v205 offset:53248
	ds_read_b128 v[226:229], v205 offset:54272
	ds_read_b128 v[230:233], v205 offset:55296
	ds_read_b128 v[234:237], v205 offset:56320
	global_load_lds_dwordx4 v[152:153], off
	s_add_i32 m0, s30, 0x2000
	s_add_u32 s30, s84, 0x80080
	v_lshl_add_u64 v[152:153], v[188:189], 0, s[62:63]
	s_addc_u32 s31, s85, 0
	s_add_i32 s54, s54, s92
	global_load_lds_dwordx4 v[152:153], off
	v_lshl_add_u64 v[152:153], s[30:31], 0, v[158:159]
	s_mov_b32 m0, s54
	s_nop 0
	global_load_lds_dwordx4 v[152:153], off
	v_lshl_add_u64 v[152:153], s[30:31], 0, v[154:155]
	s_add_i32 m0, s54, 0x2000
	s_nop 0
	global_load_lds_dwordx4 v[152:153], off
	v_lshl_add_u64 v[152:153], v[238:239], 0, s[62:63]
	s_mov_b32 m0, s88
	s_nop 0
	global_load_lds_dwordx4 v[152:153], off
	v_lshl_add_u64 v[152:153], v[240:241], 0, s[62:63]
	s_mov_b32 m0, s46
	s_nop 0
	global_load_lds_dwordx4 v[152:153], off
	s_waitcnt vmcnt(8)
	s_waitcnt lgkmcnt(0)
	s_barrier
	s_setprio 1
	s_waitcnt lgkmcnt(0)
	v_mfma_f32_16x16x32_bf16 v[92:95], v[128:131], v[206:209], v[92:95]
	v_mfma_f32_16x16x32_bf16 v[88:91], v[136:139], v[206:209], v[88:91]
	v_mfma_f32_16x16x32_bf16 v[84:87], v[128:131], v[214:217], v[84:87]
	v_mfma_f32_16x16x32_bf16 v[80:83], v[136:139], v[214:217], v[80:83]
	v_mfma_f32_16x16x32_bf16 v[76:79], v[128:131], v[222:225], v[76:79]
	v_mfma_f32_16x16x32_bf16 v[72:75], v[136:139], v[222:225], v[72:75]
	v_mfma_f32_16x16x32_bf16 v[60:63], v[128:131], v[230:233], v[60:63]
	v_mfma_f32_16x16x32_bf16 v[56:59], v[136:139], v[230:233], v[56:59]
	v_mfma_f32_16x16x32_bf16 v[92:95], v[132:135], v[210:213], v[92:95]
	v_mfma_f32_16x16x32_bf16 v[88:91], v[140:143], v[210:213], v[88:91]
	v_mfma_f32_16x16x32_bf16 v[84:87], v[132:135], v[218:221], v[84:87]
	v_mfma_f32_16x16x32_bf16 v[80:83], v[140:143], v[218:221], v[80:83]
	v_mfma_f32_16x16x32_bf16 v[76:79], v[132:135], v[226:229], v[76:79]
	v_mfma_f32_16x16x32_bf16 v[72:75], v[140:143], v[226:229], v[72:75]
	v_mfma_f32_16x16x32_bf16 v[60:63], v[132:135], v[234:237], v[60:63]
	v_mfma_f32_16x16x32_bf16 v[56:59], v[140:143], v[234:237], v[56:59]
	s_setprio 0
	s_setprio 1
	v_mfma_f32_16x16x32_bf16 v[28:31], v[144:147], v[206:209], v[28:31]
	v_mfma_f32_16x16x32_bf16 v[24:27], v[180:183], v[206:209], v[24:27]
	v_mfma_f32_16x16x32_bf16 v[20:23], v[144:147], v[214:217], v[20:23]
	v_mfma_f32_16x16x32_bf16 v[16:19], v[180:183], v[214:217], v[16:19]
	v_mfma_f32_16x16x32_bf16 v[12:15], v[144:147], v[222:225], v[12:15]
	v_mfma_f32_16x16x32_bf16 v[8:11], v[180:183], v[222:225], v[8:11]
	v_mfma_f32_16x16x32_bf16 v[4:7], v[144:147], v[230:233], v[4:7]
	v_mfma_f32_16x16x32_bf16 v[0:3], v[180:183], v[230:233], v[0:3]
	v_mfma_f32_16x16x32_bf16 v[28:31], v[148:151], v[210:213], v[28:31]
	v_mfma_f32_16x16x32_bf16 v[24:27], v[184:187], v[210:213], v[24:27]
	v_mfma_f32_16x16x32_bf16 v[20:23], v[148:151], v[218:221], v[20:23]
	v_mfma_f32_16x16x32_bf16 v[16:19], v[184:187], v[218:221], v[16:19]
	v_mfma_f32_16x16x32_bf16 v[12:15], v[148:151], v[226:229], v[12:15]
	v_mfma_f32_16x16x32_bf16 v[8:11], v[184:187], v[226:229], v[8:11]
	v_mfma_f32_16x16x32_bf16 v[4:7], v[148:151], v[234:237], v[4:7]
	v_mfma_f32_16x16x32_bf16 v[0:3], v[184:187], v[234:237], v[0:3]
	s_setprio 0
	s_barrier
	s_add_i32 s29, s29, 2
	s_add_u32 s82, s82, 0x100
	s_addc_u32 s83, s83, 0
	s_add_u32 vcc_lo, vcc_lo, 0x100
	s_addc_u32 vcc_hi, vcc_hi, 0
	s_cmp_gt_u32 s29, 29
	s_cbranch_scc0 .LBB0_68
	s_add_u32 s30, s75, 0x80080
	s_addc_u32 s31, s1, 0
	v_lshl_add_u64 v[152:153], s[30:31], 0, v[170:171]
	s_add_i32 m0, s94, 0xc000
	s_nop 0
	global_load_lds_dwordx4 v[152:153], off
	v_lshl_add_u64 v[152:153], s[30:31], 0, v[172:173]
	s_add_i32 m0, s94, 0xe000
	s_nop 0
	global_load_lds_dwordx4 v[152:153], off
	s_and_b64 vcc, exec, s[64:65]
	s_cbranch_vccz .LBB0_71
	s_barrier
